# GU: nt (streaming) hint on the weight-operand LDS-DMA loads so the activation panels stay in L2 across rounds
# baseline (speedup 1.0000x reference)
; #define BAR() { __builtin_amdgcn_sched_barrier(0); __builtin_amdgcn_s_barrier(); asm volatile("" ::: "memory"); __builtin_amdgcn_sched_barrier(0); }
; DI void gemm_stream2(const bf16_t* __restrict__ A, int lda, const bf16_t* __restrict__ Bt, int ldb, int K, int m0, int n0, ...
;     ...
;     const int wave = __builtin_amdgcn_readfirstlane(tid >> 6), lane = tid & 63, wm = wave >> 1, wn = wave & 1, r = lane & 15, q = lane >> 4;
;     const int sc0 = ((lane & 7) ^ (lane >> 4)) * 8, sc1 = ((lane & 7) ^ (4 | (lane >> 4))) * 8;
;     const bf16_t* ga = A + (size_t)(m0 + wave * 32 + (lane >> 3)) * lda;
;     const bf16_t* gb = Bt + (size_t)(n0 + wave * 16 + (lane >> 3)) * ldb;
;     const bf16_t* gan = An + (size_t)(m0n + wave * 32 + (lane >> 3)) * ldan;
;     const bf16_t* gbn = Btn + (size_t)(n0n + wave * 16 + (lane >> 3)) * ldbn;
;     const unsigned wa = (unsigned)wave * 4096u, wbb = 32768u + (unsigned)wave * 2048u;
;     ...
;     const int sw = r >> 1;
;     const unsigned fo0 = (unsigned)(r * 128 + ((q ^ sw) << 4)), fo1 = (unsigned)(r * 128 + (((q ^ sw) ^ 4) << 4));
;     const unsigned aoff = (unsigned)(wm * 64) * 128u, boff = 32768u + (unsigned)(wn * 64) * 128u;
;     const int nk = K / 64;
;     const int grp = wave >> 2;
;     ...
;     int st = rg.st;
;     if (!rg.primed) {
;         const int s1p = st == 2 ? 0 : st + 1;
;         BAR();
;         STAGE(st, 0);
;         STAGE(s1p, 1);
;         asm volatile("s_waitcnt vmcnt(6)" ::: "memory");
;         BAR();
;     }
;     if (grp == 1) BAR();
.Lgu_ranged:
	s_cmp_ge_u32 s51, s52
	s_cbranch_scc1 .LBB0_860
	v_and_b32_e32 v190, 63, v193
	v_and_b32_e32 v191, 15, v190
	v_lshrrev_b32_e32 v17, 4, v190
	v_lshrrev_b32_e32 v18, 3, v190
	v_and_b32_e32 v19, 7, v190
	v_xor_b32_e32 v195, v19, v17
	v_lshlrev_b32_e32 v195, 4, v195
	v_lshl_add_u32 v184, v18, 11, v195
	v_or_b32_e32 v195, 4, v17
	v_xor_b32_e32 v195, v19, v195
	v_lshlrev_b32_e32 v195, 4, v195
	v_add_u32_e32 v227, 8, v18
	v_lshl_add_u32 v185, v227, 11, v195
	v_lshrrev_b32_e32 v195, 1, v191
	v_xor_b32_e32 v195, v17, v195
	v_lshlrev_b32_e32 v195, 4, v195
	s_lshl_b32 s1, s33, 6
	v_add_u32_e32 v227, s1, v191
	v_lshl_add_u32 v186, v227, 7, v195
	v_xor_b32_e32 v187, 64, v186
	v_mul_u32_u24_e32 v228, 0x1600, v227
	s_lshl_b32 s1, s36, 5
	v_add_u32_e32 v227, s1, v191
	v_lshl_add_u32 v188, v227, 7, v195
	v_add_u32_e32 v188, 0x10000, v188
	v_xor_b32_e32 v189, 64, v188
	v_lshl_add_u32 v229, v17, 3, s1
	v_add_u32_e32 v237, v228, v229
	v_and_b32_e32 v227, 1, v17
	v_mul_u32_u24_e32 v227, 0x15ff8, v227
	v_add_u32_e32 v237, v237, v227
	s_mul_i32 s1, s51, 0x1745e
	s_lshr_b32 s2, s1, 24
	s_mul_i32 s1, s2, 0xb0
	s_sub_u32 s1, s51, s1
	s_lshr_b32 s3, s1, 3
	s_and_b32 s37, s1, 7
	s_cmp_lt_u32 s2, 8
	s_cselect_b32 s58, s3, s1
	s_cselect_b32 s37, s37, 0
	s_lshl_b32 s2, s2, 3
	s_add_i32 s57, s2, s37
	s_lshl_b32 s1, s57, 19
	s_lshl_b32 s2, s10, 15
	s_add_u32 s1, s1, s2
	s_add_u32 s1, s1, 0x3240000
	s_add_u32 s66, s88, s1
	s_addc_u32 s67, s89, 0
	s_add_u32 s68, s66, 0x40000
	s_addc_u32 s69, s67, 0
	s_lshl_b32 s1, s58, 19
	s_add_u32 s1, s1, s2
	s_add_u32 s1, s1, s61
	s_add_u32 s70, s88, s1
	s_addc_u32 s71, s89, 0
	s_add_u32 s72, s70, 0x40000
	s_addc_u32 s73, s71, 0
	s_add_i32 m0, s39, 0x10000
	s_nop 0
	global_load_lds_dwordx4 v184, s[70:71] nt
	s_add_i32 m0, s39, 0x10400
	s_nop 0
	global_load_lds_dwordx4 v185, s[70:71] nt
	s_add_u32 s70, s70, 0x80
	s_addc_u32 s71, s71, 0
	s_add_i32 m0, s39, 0x0
	s_nop 0
	global_load_lds_dwordx4 v184, s[66:67]
	s_add_i32 m0, s39, 0x400
	s_nop 0
	global_load_lds_dwordx4 v185, s[66:67]
	s_add_u32 s66, s66, 0x80
	s_addc_u32 s67, s67, 0
	s_add_i32 m0, s39, 0x14000
	s_nop 0
	global_load_lds_dwordx4 v184, s[72:73] nt
	s_add_i32 m0, s39, 0x14400
	s_nop 0
	global_load_lds_dwordx4 v185, s[72:73] nt
	s_add_u32 s72, s72, 0x80
	s_addc_u32 s73, s73, 0
	s_add_i32 m0, s39, 0x4000
	s_nop 0
	global_load_lds_dwordx4 v184, s[68:69]
	s_add_i32 m0, s39, 0x4400
	s_nop 0
	global_load_lds_dwordx4 v185, s[68:69]
	s_add_u32 s68, s68, 0x80
	s_addc_u32 s69, s69, 0
	s_add_i32 m0, s39, 0x18000
	s_nop 0
	global_load_lds_dwordx4 v184, s[70:71] nt
	s_add_i32 m0, s39, 0x18400
	s_nop 0
	global_load_lds_dwordx4 v185, s[70:71] nt
	s_add_u32 s70, s70, 0x80
	s_addc_u32 s71, s71, 0
	s_add_i32 m0, s39, 0x8000
	s_nop 0
	global_load_lds_dwordx4 v184, s[66:67]
	s_add_i32 m0, s39, 0x8400
	s_nop 0
	global_load_lds_dwordx4 v185, s[66:67]
	s_add_u32 s66, s66, 0x80
	s_addc_u32 s67, s67, 0
	s_add_i32 m0, s39, 0x1c000
	s_nop 0
	global_load_lds_dwordx4 v184, s[72:73] nt
	s_add_i32 m0, s39, 0x1c400
	s_nop 0
	global_load_lds_dwordx4 v185, s[72:73] nt
	s_add_u32 s72, s72, 0x80
	s_addc_u32 s73, s73, 0
	s_waitcnt vmcnt(8)
	s_barrier
	s_cmp_eq_u32 s33, 0
	s_cbranch_scc1 .Lgu_lead
	s_barrier

; #define LAS __attribute__((address_space(3)))
; #define BAR() { __builtin_amdgcn_sched_barrier(0); __builtin_amdgcn_s_barrier(); asm volatile("" ::: "memory"); __builtin_amdgcn_sched_barrier(0); }
; DI void gemm_stream2(const bf16_t* __restrict__ A, int lda, const bf16_t* __restrict__ Bt, int ldb, int K, int m0, int n0, ...
;     ...
;     for (int kt = 0; kt < nk; ++kt) {
;         const bool pf = (kt + 2 < nk) || has_next, more = (kt + 1 < nk) || has_next;
;         const bf16_t* pa = (kt + 2 < nk) ? ga + (kt + 2) * 64 : gan + (kt + 2 - nk) * 64;
;         const bf16_t* pb = (kt + 2 < nk) ? gb + (kt + 2) * 64 : gbn + (kt + 2 - nk) * 64;
;         const int plda = (kt + 2 < nk) ? lda : ldan, pldb = (kt + 2 < nk) ? ldb : ldbn;
;         const int s2 = st >= 1 ? st - 1 : 2;
;         const LAS char* base = lds + st * 49152;
; #pragma unroll
;         for (int ks = 0; ks < 2; ++ks) {
;             const unsigned fo = ks ? fo1 : fo0;
;             bf16x8 af[4], bfr[4];
; #pragma unroll
;             for (int i = 0; i < 4; ++i) { af[i] = *(const LAS bf16x8*)(base + aoff + i * 2048 + fo); bfr[i] = *(const LAS bf16x8*)(base + boff + i * 2048 + fo); }
;             if (ks == 1 && more) { if (pf) asm volatile("s_waitcnt vmcnt(3)" ::: "memory"); else asm volatile("s_waitcnt vmcnt(0)" ::: "memory"); }
;             if (pf) { PIECE(s2, ks * 3 + 0); PIECE(s2, ks * 3 + 1); PIECE(s2, ks * 3 + 2); }
;             asm volatile("s_waitcnt lgkmcnt(0)" ::: "memory");
;             BAR();
;             __builtin_amdgcn_s_setprio(1);
; #pragma unroll
;             for (int mi = 0; mi < 4; ++mi)
; #pragma unroll
;                 for (int ni = 0; ni < 4; ++ni) acc[mi][ni] = __builtin_amdgcn_mfma_f32_16x16x32_bf16(bfr[ni], af[mi], acc[mi][ni], 0, 0, 0);
;             __builtin_amdgcn_s_setprio(0);
;             BAR();
;         }
.Lgu_nosw1:
	s_add_i32 m0, s39, 0x10000
	s_nop 0
	global_load_lds_dwordx4 v184, s[70:71] nt
	s_add_i32 m0, s39, 0x10400
	s_nop 0
	global_load_lds_dwordx4 v185, s[70:71] nt
	s_add_u32 s70, s70, 0x80
	s_addc_u32 s71, s71, 0
	s_add_i32 m0, s39, 0x0
	s_nop 0
	global_load_lds_dwordx4 v184, s[66:67]
	s_add_i32 m0, s39, 0x400
	s_nop 0
	global_load_lds_dwordx4 v185, s[66:67]
	s_add_u32 s66, s66, 0x80
	s_addc_u32 s67, s67, 0
	s_add_i32 m0, s39, 0x14000
	s_nop 0
	global_load_lds_dwordx4 v184, s[72:73] nt
	s_add_i32 m0, s39, 0x14400
	s_nop 0
	global_load_lds_dwordx4 v185, s[72:73] nt
	s_add_u32 s72, s72, 0x80
	s_addc_u32 s73, s73, 0
	s_waitcnt lgkmcnt(0)
	s_waitcnt vmcnt(8)
	s_barrier
	s_setprio 1
	v_mfma_f32_16x16x32_bf16 v[88:91], v[0:3], v[152:155], v[88:91]
	v_mfma_f32_16x16x32_bf16 v[92:95], v[8:11], v[152:155], v[92:95]
	v_mfma_f32_16x16x32_bf16 v[96:99], v[0:3], v[160:163], v[96:99]
	v_mfma_f32_16x16x32_bf16 v[100:103], v[8:11], v[160:163], v[100:103]
	v_mfma_f32_16x16x32_bf16 v[104:107], v[0:3], v[168:171], v[104:107]
	v_mfma_f32_16x16x32_bf16 v[108:111], v[8:11], v[168:171], v[108:111]
	v_mfma_f32_16x16x32_bf16 v[112:115], v[0:3], v[176:179], v[112:115]
	v_mfma_f32_16x16x32_bf16 v[116:119], v[8:11], v[176:179], v[116:119]
	v_mfma_f32_16x16x32_bf16 v[88:91], v[4:7], v[156:159], v[88:91]
	v_mfma_f32_16x16x32_bf16 v[92:95], v[12:15], v[156:159], v[92:95]
	v_mfma_f32_16x16x32_bf16 v[96:99], v[4:7], v[164:167], v[96:99]
	v_mfma_f32_16x16x32_bf16 v[100:103], v[12:15], v[164:167], v[100:103]
	v_mfma_f32_16x16x32_bf16 v[104:107], v[4:7], v[172:175], v[104:107]
	v_mfma_f32_16x16x32_bf16 v[108:111], v[12:15], v[172:175], v[108:111]
	v_mfma_f32_16x16x32_bf16 v[112:115], v[4:7], v[180:183], v[112:115]
	v_mfma_f32_16x16x32_bf16 v[116:119], v[12:15], v[180:183], v[116:119]
	v_mfma_f32_16x16x32_bf16 v[120:123], v[196:199], v[152:155], v[120:123]
	v_mfma_f32_16x16x32_bf16 v[124:127], v[204:207], v[152:155], v[124:127]
	v_mfma_f32_16x16x32_bf16 v[128:131], v[196:199], v[160:163], v[128:131]
	v_mfma_f32_16x16x32_bf16 v[132:135], v[204:207], v[160:163], v[132:135]
	v_mfma_f32_16x16x32_bf16 v[136:139], v[196:199], v[168:171], v[136:139]
	v_mfma_f32_16x16x32_bf16 v[140:143], v[204:207], v[168:171], v[140:143]
	v_mfma_f32_16x16x32_bf16 v[144:147], v[196:199], v[176:179], v[144:147]
	v_mfma_f32_16x16x32_bf16 v[148:151], v[204:207], v[176:179], v[148:151]
	v_mfma_f32_16x16x32_bf16 v[120:123], v[200:203], v[156:159], v[120:123]
	v_mfma_f32_16x16x32_bf16 v[124:127], v[208:211], v[156:159], v[124:127]
	v_mfma_f32_16x16x32_bf16 v[128:131], v[200:203], v[164:167], v[128:131]
	v_mfma_f32_16x16x32_bf16 v[132:135], v[208:211], v[164:167], v[132:135]
	v_mfma_f32_16x16x32_bf16 v[136:139], v[200:203], v[172:175], v[136:139]
	v_mfma_f32_16x16x32_bf16 v[140:143], v[208:211], v[172:175], v[140:143]
	v_mfma_f32_16x16x32_bf16 v[144:147], v[200:203], v[180:183], v[144:147]
	v_mfma_f32_16x16x32_bf16 v[148:151], v[208:211], v[180:183], v[148:151]
	s_setprio 0
	s_barrier
	ds_read_b128 v[0:3], v188 offset:32784
	ds_read_b128 v[4:7], v189 offset:32784
	ds_read_b128 v[8:11], v188 offset:34832
	ds_read_b128 v[12:15], v189 offset:34832
	ds_read_b128 v[196:199], v188 offset:49168
	ds_read_b128 v[200:203], v189 offset:49168
	ds_read_b128 v[204:207], v188 offset:51216
	ds_read_b128 v[208:211], v189 offset:51216
	ds_read_b128 v[152:155], v186 offset:32784
	ds_read_b128 v[156:159], v187 offset:32784
	ds_read_b128 v[160:163], v186 offset:34832
	ds_read_b128 v[164:167], v187 offset:34832
	ds_read_b128 v[168:171], v186 offset:36880
	ds_read_b128 v[172:175], v187 offset:36880
	ds_read_b128 v[176:179], v186 offset:38928
	ds_read_b128 v[180:183], v187 offset:38928
	s_cmp_lg_u32 s0, s54
	s_cbranch_scc1 .Lgu_nosw2
	s_mov_b64 s[68:69], s[78:79]
.Lgu_nosw2:
	s_add_i32 m0, s39, 0x4000
	s_nop 0
	global_load_lds_dwordx4 v184, s[68:69]
	s_add_i32 m0, s39, 0x4400
	s_nop 0
	global_load_lds_dwordx4 v185, s[68:69]
	s_add_u32 s68, s68, 0x80
	s_addc_u32 s69, s69, 0
	s_waitcnt lgkmcnt(0)
	s_waitcnt vmcnt(8)
	s_barrier
	s_setprio 1
	v_mfma_f32_16x16x32_bf16 v[24:27], v[0:3], v[152:155], v[24:27]
	v_mfma_f32_16x16x32_bf16 v[28:31], v[8:11], v[152:155], v[28:31]
	v_mfma_f32_16x16x32_bf16 v[32:35], v[0:3], v[160:163], v[32:35]
	v_mfma_f32_16x16x32_bf16 v[36:39], v[8:11], v[160:163], v[36:39]
	v_mfma_f32_16x16x32_bf16 v[40:43], v[0:3], v[168:171], v[40:43]
	v_mfma_f32_16x16x32_bf16 v[44:47], v[8:11], v[168:171], v[44:47]
	v_mfma_f32_16x16x32_bf16 v[48:51], v[0:3], v[176:179], v[48:51]
	v_mfma_f32_16x16x32_bf16 v[52:55], v[8:11], v[176:179], v[52:55]
	v_mfma_f32_16x16x32_bf16 v[24:27], v[4:7], v[156:159], v[24:27]
	v_mfma_f32_16x16x32_bf16 v[28:31], v[12:15], v[156:159], v[28:31]
	v_mfma_f32_16x16x32_bf16 v[32:35], v[4:7], v[164:167], v[32:35]
	v_mfma_f32_16x16x32_bf16 v[36:39], v[12:15], v[164:167], v[36:39]
	v_mfma_f32_16x16x32_bf16 v[40:43], v[4:7], v[172:175], v[40:43]
	v_mfma_f32_16x16x32_bf16 v[44:47], v[12:15], v[172:175], v[44:47]
	v_mfma_f32_16x16x32_bf16 v[48:51], v[4:7], v[180:183], v[48:51]
	v_mfma_f32_16x16x32_bf16 v[52:55], v[12:15], v[180:183], v[52:55]
	v_mfma_f32_16x16x32_bf16 v[56:59], v[196:199], v[152:155], v[56:59]
	v_mfma_f32_16x16x32_bf16 v[60:63], v[204:207], v[152:155], v[60:63]
	v_mfma_f32_16x16x32_bf16 v[64:67], v[196:199], v[160:163], v[64:67]
	v_mfma_f32_16x16x32_bf16 v[68:71], v[204:207], v[160:163], v[68:71]
	v_mfma_f32_16x16x32_bf16 v[72:75], v[196:199], v[168:171], v[72:75]
	v_mfma_f32_16x16x32_bf16 v[76:79], v[204:207], v[168:171], v[76:79]
	v_mfma_f32_16x16x32_bf16 v[80:83], v[196:199], v[176:179], v[80:83]
	v_mfma_f32_16x16x32_bf16 v[84:87], v[204:207], v[176:179], v[84:87]
	v_mfma_f32_16x16x32_bf16 v[56:59], v[200:203], v[156:159], v[56:59]
	v_mfma_f32_16x16x32_bf16 v[60:63], v[208:211], v[156:159], v[60:63]
	v_mfma_f32_16x16x32_bf16 v[64:67], v[200:203], v[164:167], v[64:67]
	v_mfma_f32_16x16x32_bf16 v[68:71], v[208:211], v[164:167], v[68:71]
	v_mfma_f32_16x16x32_bf16 v[72:75], v[200:203], v[172:175], v[72:75]
	v_mfma_f32_16x16x32_bf16 v[76:79], v[208:211], v[172:175], v[76:79]
	v_mfma_f32_16x16x32_bf16 v[80:83], v[200:203], v[180:183], v[80:83]
	v_mfma_f32_16x16x32_bf16 v[84:87], v[208:211], v[180:183], v[84:87]
	s_setprio 0
	s_barrier
; #define LAS __attribute__((address_space(3)))
; #define BAR() { __builtin_amdgcn_sched_barrier(0); __builtin_amdgcn_s_barrier(); asm volatile("" ::: "memory"); __builtin_amdgcn_sched_barrier(0); }
; DI void gemm_stream2(const bf16_t* __restrict__ A, int lda, const bf16_t* __restrict__ Bt, int ldb, int K, int m0, int n0, ...
;     ...
;     for (int kt = 0; kt < nk; ++kt) {
;         const bool pf = (kt + 2 < nk) || has_next, more = (kt + 1 < nk) || has_next;
;         const bf16_t* pa = (kt + 2 < nk) ? ga + (kt + 2) * 64 : gan + (kt + 2 - nk) * 64;
;         const bf16_t* pb = (kt + 2 < nk) ? gb + (kt + 2) * 64 : gbn + (kt + 2 - nk) * 64;
;         const int plda = (kt + 2 < nk) ? lda : ldan, pldb = (kt + 2 < nk) ? ldb : ldbn;
;         const int s2 = st >= 1 ? st - 1 : 2;
;         const LAS char* base = lds + st * 49152;
; #pragma unroll
;         for (int ks = 0; ks < 2; ++ks) {
;             const unsigned fo = ks ? fo1 : fo0;
;             bf16x8 af[4], bfr[4];
; #pragma unroll
;             for (int i = 0; i < 4; ++i) { af[i] = *(const LAS bf16x8*)(base + aoff + i * 2048 + fo); bfr[i] = *(const LAS bf16x8*)(base + boff + i * 2048 + fo); }
;             if (ks == 1 && more) { if (pf) asm volatile("s_waitcnt vmcnt(3)" ::: "memory"); else asm volatile("s_waitcnt vmcnt(0)" ::: "memory"); }
;             if (pf) { PIECE(s2, ks * 3 + 0); PIECE(s2, ks * 3 + 1); PIECE(s2, ks * 3 + 2); }
;             asm volatile("s_waitcnt lgkmcnt(0)" ::: "memory");
;             BAR();
;             __builtin_amdgcn_s_setprio(1);
; #pragma unroll
;             for (int mi = 0; mi < 4; ++mi)
; #pragma unroll
;                 for (int ni = 0; ni < 4; ++ni) acc[mi][ni] = __builtin_amdgcn_mfma_f32_16x16x32_bf16(bfr[ni], af[mi], acc[mi][ni], 0, 0, 0);
;             __builtin_amdgcn_s_setprio(0);
;             BAR();
;         }
;         st = st == 2 ? 0 : st + 1;
;     }
;     if (grp == 0) BAR();
	ds_read_b128 v[152:155], v186 offset:49168
	ds_read_b128 v[156:159], v187 offset:49168
	ds_read_b128 v[160:163], v186 offset:51216
	ds_read_b128 v[164:167], v187 offset:51216
	ds_read_b128 v[168:171], v186 offset:53264
	ds_read_b128 v[172:175], v187 offset:53264
	ds_read_b128 v[176:179], v186 offset:55312
	ds_read_b128 v[180:183], v187 offset:55312
	s_add_i32 m0, s39, 0x18000
	s_nop 0
	global_load_lds_dwordx4 v184, s[70:71] nt
	s_add_i32 m0, s39, 0x18400
	s_nop 0
	global_load_lds_dwordx4 v185, s[70:71] nt
	s_add_u32 s70, s70, 0x80
	s_addc_u32 s71, s71, 0
	s_add_i32 m0, s39, 0x8000
	s_nop 0
	global_load_lds_dwordx4 v184, s[66:67]
	s_add_i32 m0, s39, 0x8400
	s_nop 0
	global_load_lds_dwordx4 v185, s[66:67]
	s_add_u32 s66, s66, 0x80
	s_addc_u32 s67, s67, 0
	s_add_i32 m0, s39, 0x1c000
	s_nop 0
	global_load_lds_dwordx4 v184, s[72:73] nt
	s_add_i32 m0, s39, 0x1c400
	s_nop 0
	global_load_lds_dwordx4 v185, s[72:73] nt
	s_add_u32 s72, s72, 0x80
	s_addc_u32 s73, s73, 0
	s_waitcnt lgkmcnt(0)
	s_waitcnt vmcnt(8)
	s_barrier
	s_setprio 1
	v_mfma_f32_16x16x32_bf16 v[88:91], v[0:3], v[152:155], v[88:91]
	v_mfma_f32_16x16x32_bf16 v[92:95], v[8:11], v[152:155], v[92:95]
	v_mfma_f32_16x16x32_bf16 v[96:99], v[0:3], v[160:163], v[96:99]
	v_mfma_f32_16x16x32_bf16 v[100:103], v[8:11], v[160:163], v[100:103]
	v_mfma_f32_16x16x32_bf16 v[104:107], v[0:3], v[168:171], v[104:107]
	v_mfma_f32_16x16x32_bf16 v[108:111], v[8:11], v[168:171], v[108:111]
	v_mfma_f32_16x16x32_bf16 v[112:115], v[0:3], v[176:179], v[112:115]
	v_mfma_f32_16x16x32_bf16 v[116:119], v[8:11], v[176:179], v[116:119]
	v_mfma_f32_16x16x32_bf16 v[88:91], v[4:7], v[156:159], v[88:91]
	v_mfma_f32_16x16x32_bf16 v[92:95], v[12:15], v[156:159], v[92:95]
	v_mfma_f32_16x16x32_bf16 v[96:99], v[4:7], v[164:167], v[96:99]
	v_mfma_f32_16x16x32_bf16 v[100:103], v[12:15], v[164:167], v[100:103]
	v_mfma_f32_16x16x32_bf16 v[104:107], v[4:7], v[172:175], v[104:107]
	v_mfma_f32_16x16x32_bf16 v[108:111], v[12:15], v[172:175], v[108:111]
	v_mfma_f32_16x16x32_bf16 v[112:115], v[4:7], v[180:183], v[112:115]
	v_mfma_f32_16x16x32_bf16 v[116:119], v[12:15], v[180:183], v[116:119]
	v_mfma_f32_16x16x32_bf16 v[120:123], v[196:199], v[152:155], v[120:123]
	v_mfma_f32_16x16x32_bf16 v[124:127], v[204:207], v[152:155], v[124:127]
	v_mfma_f32_16x16x32_bf16 v[128:131], v[196:199], v[160:163], v[128:131]
	v_mfma_f32_16x16x32_bf16 v[132:135], v[204:207], v[160:163], v[132:135]
	v_mfma_f32_16x16x32_bf16 v[136:139], v[196:199], v[168:171], v[136:139]
	v_mfma_f32_16x16x32_bf16 v[140:143], v[204:207], v[168:171], v[140:143]
	v_mfma_f32_16x16x32_bf16 v[144:147], v[196:199], v[176:179], v[144:147]
	v_mfma_f32_16x16x32_bf16 v[148:151], v[204:207], v[176:179], v[148:151]
	v_mfma_f32_16x16x32_bf16 v[120:123], v[200:203], v[156:159], v[120:123]
	v_mfma_f32_16x16x32_bf16 v[124:127], v[208:211], v[156:159], v[124:127]
	v_mfma_f32_16x16x32_bf16 v[128:131], v[200:203], v[164:167], v[128:131]
	v_mfma_f32_16x16x32_bf16 v[132:135], v[208:211], v[164:167], v[132:135]
	v_mfma_f32_16x16x32_bf16 v[136:139], v[200:203], v[172:175], v[136:139]
	v_mfma_f32_16x16x32_bf16 v[140:143], v[208:211], v[172:175], v[140:143]
	v_mfma_f32_16x16x32_bf16 v[144:147], v[200:203], v[180:183], v[144:147]
	v_mfma_f32_16x16x32_bf16 v[148:151], v[208:211], v[180:183], v[148:151]
	s_setprio 0
	s_barrier
	s_sub_u32 s0, s0, 1
	s_cmp_lg_u32 s0, 0
	s_cbranch_scc1 .Lgu_kloop
	s_cmp_lg_u32 s54, 0
	s_cbranch_scc1 .Lgu_epi
	ds_read_b128 v[0:3], v188 offset:16
	ds_read_b128 v[4:7], v189 offset:16
	ds_read_b128 v[8:11], v188 offset:2064
	ds_read_b128 v[12:15], v189 offset:2064
	ds_read_b128 v[196:199], v188 offset:16400
	ds_read_b128 v[200:203], v189 offset:16400
	ds_read_b128 v[204:207], v188 offset:18448
	ds_read_b128 v[208:211], v189 offset:18448
	ds_read_b128 v[152:155], v186 offset:16
	ds_read_b128 v[156:159], v187 offset:16
	ds_read_b128 v[160:163], v186 offset:2064
	ds_read_b128 v[164:167], v187 offset:2064
	ds_read_b128 v[168:171], v186 offset:4112
	ds_read_b128 v[172:175], v187 offset:4112
	ds_read_b128 v[176:179], v186 offset:6160
	ds_read_b128 v[180:183], v187 offset:6160
	s_add_i32 m0, s39, 0xc000
	s_nop 0
	global_load_lds_dwordx4 v184, s[68:69]
	s_add_i32 m0, s39, 0xc400
	s_nop 0
	global_load_lds_dwordx4 v185, s[68:69]
	s_add_u32 s68, s68, 0x80
	s_addc_u32 s69, s69, 0
	s_waitcnt lgkmcnt(0)
	s_waitcnt vmcnt(8)
	s_barrier
	s_setprio 1
	v_mfma_f32_16x16x32_bf16 v[24:27], v[0:3], v[152:155], v[24:27]
	v_mfma_f32_16x16x32_bf16 v[28:31], v[8:11], v[152:155], v[28:31]
	v_mfma_f32_16x16x32_bf16 v[32:35], v[0:3], v[160:163], v[32:35]
	v_mfma_f32_16x16x32_bf16 v[36:39], v[8:11], v[160:163], v[36:39]
	v_mfma_f32_16x16x32_bf16 v[40:43], v[0:3], v[168:171], v[40:43]
	v_mfma_f32_16x16x32_bf16 v[44:47], v[8:11], v[168:171], v[44:47]
	v_mfma_f32_16x16x32_bf16 v[48:51], v[0:3], v[176:179], v[48:51]
	v_mfma_f32_16x16x32_bf16 v[52:55], v[8:11], v[176:179], v[52:55]
	v_mfma_f32_16x16x32_bf16 v[24:27], v[4:7], v[156:159], v[24:27]
	v_mfma_f32_16x16x32_bf16 v[28:31], v[12:15], v[156:159], v[28:31]
	v_mfma_f32_16x16x32_bf16 v[32:35], v[4:7], v[164:167], v[32:35]
	v_mfma_f32_16x16x32_bf16 v[36:39], v[12:15], v[164:167], v[36:39]
	v_mfma_f32_16x16x32_bf16 v[40:43], v[4:7], v[172:175], v[40:43]
	v_mfma_f32_16x16x32_bf16 v[44:47], v[12:15], v[172:175], v[44:47]
	v_mfma_f32_16x16x32_bf16 v[48:51], v[4:7], v[180:183], v[48:51]
	v_mfma_f32_16x16x32_bf16 v[52:55], v[12:15], v[180:183], v[52:55]
	v_mfma_f32_16x16x32_bf16 v[56:59], v[196:199], v[152:155], v[56:59]
	v_mfma_f32_16x16x32_bf16 v[60:63], v[204:207], v[152:155], v[60:63]
	v_mfma_f32_16x16x32_bf16 v[64:67], v[196:199], v[160:163], v[64:67]
	v_mfma_f32_16x16x32_bf16 v[68:71], v[204:207], v[160:163], v[68:71]
	v_mfma_f32_16x16x32_bf16 v[72:75], v[196:199], v[168:171], v[72:75]
	v_mfma_f32_16x16x32_bf16 v[76:79], v[204:207], v[168:171], v[76:79]
	v_mfma_f32_16x16x32_bf16 v[80:83], v[196:199], v[176:179], v[80:83]
	v_mfma_f32_16x16x32_bf16 v[84:87], v[204:207], v[176:179], v[84:87]
	v_mfma_f32_16x16x32_bf16 v[56:59], v[200:203], v[156:159], v[56:59]
	v_mfma_f32_16x16x32_bf16 v[60:63], v[208:211], v[156:159], v[60:63]
	v_mfma_f32_16x16x32_bf16 v[64:67], v[200:203], v[164:167], v[64:67]
	v_mfma_f32_16x16x32_bf16 v[68:71], v[208:211], v[164:167], v[68:71]
	v_mfma_f32_16x16x32_bf16 v[72:75], v[200:203], v[172:175], v[72:75]
	v_mfma_f32_16x16x32_bf16 v[76:79], v[208:211], v[172:175], v[76:79]
	v_mfma_f32_16x16x32_bf16 v[80:83], v[200:203], v[180:183], v[80:83]
	v_mfma_f32_16x16x32_bf16 v[84:87], v[208:211], v[180:183], v[84:87]
	s_setprio 0
	s_barrier
; #define LAS __attribute__((address_space(3)))
; #define BAR() { __builtin_amdgcn_sched_barrier(0); __builtin_amdgcn_s_barrier(); asm volatile("" ::: "memory"); __builtin_amdgcn_sched_barrier(0); }
; DI void gemm_stream2(const bf16_t* __restrict__ A, int lda, const bf16_t* __restrict__ Bt, int ldb, int K, int m0, int n0, ...
;     ...
; #pragma unroll
;         for (int ks = 0; ks < 2; ++ks) {
;             const unsigned fo = ks ? fo1 : fo0;
;             bf16x8 af[4], bfr[4];
; #pragma unroll
;             for (int i = 0; i < 4; ++i) { af[i] = *(const LAS bf16x8*)(base + aoff + i * 2048 + fo); bfr[i] = *(const LAS bf16x8*)(base + boff + i * 2048 + fo); }
;             if (ks == 1 && more) { if (pf) asm volatile("s_waitcnt vmcnt(3)" ::: "memory"); else asm volatile("s_waitcnt vmcnt(0)" ::: "memory"); }
;             if (pf) { PIECE(s2, ks * 3 + 0); PIECE(s2, ks * 3 + 1); PIECE(s2, ks * 3 + 2); }
;             asm volatile("s_waitcnt lgkmcnt(0)" ::: "memory");
;             BAR();
;             __builtin_amdgcn_s_setprio(1);
; #pragma unroll
;             for (int mi = 0; mi < 4; ++mi)
; #pragma unroll
;                 for (int ni = 0; ni < 4; ++ni) acc[mi][ni] = __builtin_amdgcn_mfma_f32_16x16x32_bf16(bfr[ni], af[mi], acc[mi][ni], 0, 0, 0);
;             __builtin_amdgcn_s_setprio(0);
;             BAR();
;         }
	ds_read_b128 v[152:155], v186 offset:16400
	ds_read_b128 v[156:159], v187 offset:16400
	ds_read_b128 v[160:163], v186 offset:18448
	ds_read_b128 v[164:167], v187 offset:18448
	ds_read_b128 v[168:171], v186 offset:20496
	ds_read_b128 v[172:175], v187 offset:20496
	ds_read_b128 v[176:179], v186 offset:22544
	ds_read_b128 v[180:183], v187 offset:22544
	s_waitcnt lgkmcnt(0)
	s_waitcnt vmcnt(2)
	s_barrier
	s_setprio 1
	v_mfma_f32_16x16x32_bf16 v[88:91], v[0:3], v[152:155], v[88:91]
	v_mfma_f32_16x16x32_bf16 v[92:95], v[8:11], v[152:155], v[92:95]
	v_mfma_f32_16x16x32_bf16 v[96:99], v[0:3], v[160:163], v[96:99]
	v_mfma_f32_16x16x32_bf16 v[100:103], v[8:11], v[160:163], v[100:103]
	v_mfma_f32_16x16x32_bf16 v[104:107], v[0:3], v[168:171], v[104:107]
	v_mfma_f32_16x16x32_bf16 v[108:111], v[8:11], v[168:171], v[108:111]
	v_mfma_f32_16x16x32_bf16 v[112:115], v[0:3], v[176:179], v[112:115]
	v_mfma_f32_16x16x32_bf16 v[116:119], v[8:11], v[176:179], v[116:119]
	v_mfma_f32_16x16x32_bf16 v[88:91], v[4:7], v[156:159], v[88:91]
	v_mfma_f32_16x16x32_bf16 v[92:95], v[12:15], v[156:159], v[92:95]
	v_mfma_f32_16x16x32_bf16 v[96:99], v[4:7], v[164:167], v[96:99]
	v_mfma_f32_16x16x32_bf16 v[100:103], v[12:15], v[164:167], v[100:103]
	v_mfma_f32_16x16x32_bf16 v[104:107], v[4:7], v[172:175], v[104:107]
	v_mfma_f32_16x16x32_bf16 v[108:111], v[12:15], v[172:175], v[108:111]
	v_mfma_f32_16x16x32_bf16 v[112:115], v[4:7], v[180:183], v[112:115]
	v_mfma_f32_16x16x32_bf16 v[116:119], v[12:15], v[180:183], v[116:119]
	v_mfma_f32_16x16x32_bf16 v[120:123], v[196:199], v[152:155], v[120:123]
	v_mfma_f32_16x16x32_bf16 v[124:127], v[204:207], v[152:155], v[124:127]
	v_mfma_f32_16x16x32_bf16 v[128:131], v[196:199], v[160:163], v[128:131]
	v_mfma_f32_16x16x32_bf16 v[132:135], v[204:207], v[160:163], v[132:135]
	v_mfma_f32_16x16x32_bf16 v[136:139], v[196:199], v[168:171], v[136:139]
	v_mfma_f32_16x16x32_bf16 v[140:143], v[204:207], v[168:171], v[140:143]
	v_mfma_f32_16x16x32_bf16 v[144:147], v[196:199], v[176:179], v[144:147]
	v_mfma_f32_16x16x32_bf16 v[148:151], v[204:207], v[176:179], v[148:151]
	v_mfma_f32_16x16x32_bf16 v[120:123], v[200:203], v[156:159], v[120:123]
	v_mfma_f32_16x16x32_bf16 v[124:127], v[208:211], v[156:159], v[124:127]
	v_mfma_f32_16x16x32_bf16 v[128:131], v[200:203], v[164:167], v[128:131]
	v_mfma_f32_16x16x32_bf16 v[132:135], v[208:211], v[164:167], v[132:135]
	v_mfma_f32_16x16x32_bf16 v[136:139], v[200:203], v[172:175], v[136:139]
	v_mfma_f32_16x16x32_bf16 v[140:143], v[208:211], v[172:175], v[140:143]
	v_mfma_f32_16x16x32_bf16 v[144:147], v[200:203], v[180:183], v[144:147]
	v_mfma_f32_16x16x32_bf16 v[148:151], v[208:211], v[180:183], v[148:151]
	s_setprio 0
	s_barrier
	ds_read_b128 v[0:3], v188 offset:32784
	ds_read_b128 v[4:7], v189 offset:32784
	ds_read_b128 v[8:11], v188 offset:34832
	ds_read_b128 v[12:15], v189 offset:34832
	ds_read_b128 v[196:199], v188 offset:49168
	ds_read_b128 v[200:203], v189 offset:49168
	ds_read_b128 v[204:207], v188 offset:51216
	ds_read_b128 v[208:211], v189 offset:51216
	ds_read_b128 v[152:155], v186 offset:32784
	ds_read_b128 v[156:159], v187 offset:32784
	ds_read_b128 v[160:163], v186 offset:34832
	ds_read_b128 v[164:167], v187 offset:34832
	ds_read_b128 v[168:171], v186 offset:36880
	ds_read_b128 v[172:175], v187 offset:36880
	ds_read_b128 v[176:179], v186 offset:38928
	ds_read_b128 v[180:183], v187 offset:38928
	s_waitcnt lgkmcnt(0)
	s_waitcnt vmcnt(0)
	s_barrier
; #define LAS __attribute__((address_space(3)))
; #define BAR() { __builtin_amdgcn_sched_barrier(0); __builtin_amdgcn_s_barrier(); asm volatile("" ::: "memory"); __builtin_amdgcn_sched_barrier(0); }
; DI void gemm_stream2(const bf16_t* __restrict__ A, int lda, const bf16_t* __restrict__ Bt, int ldb, int K, int m0, int n0, ...
;     ...
; #pragma unroll
;         for (int ks = 0; ks < 2; ++ks) {
;             const unsigned fo = ks ? fo1 : fo0;
;             bf16x8 af[4], bfr[4];
; #pragma unroll
;             for (int i = 0; i < 4; ++i) { af[i] = *(const LAS bf16x8*)(base + aoff + i * 2048 + fo); bfr[i] = *(const LAS bf16x8*)(base + boff + i * 2048 + fo); }
;             if (ks == 1 && more) { if (pf) asm volatile("s_waitcnt vmcnt(3)" ::: "memory"); else asm volatile("s_waitcnt vmcnt(0)" ::: "memory"); }
;             if (pf) { PIECE(s2, ks * 3 + 0); PIECE(s2, ks * 3 + 1); PIECE(s2, ks * 3 + 2); }
;             asm volatile("s_waitcnt lgkmcnt(0)" ::: "memory");
;             BAR();
;             __builtin_amdgcn_s_setprio(1);
; #pragma unroll
;             for (int mi = 0; mi < 4; ++mi)
; #pragma unroll
;                 for (int ni = 0; ni < 4; ++ni) acc[mi][ni] = __builtin_amdgcn_mfma_f32_16x16x32_bf16(bfr[ni], af[mi], acc[mi][ni], 0, 0, 0);
;             __builtin_amdgcn_s_setprio(0);
;             BAR();
;         }
;         st = st == 2 ? 0 : st + 1;
;     }
;     if (grp == 0) BAR();
	s_setprio 1
	v_mfma_f32_16x16x32_bf16 v[24:27], v[0:3], v[152:155], v[24:27]
	v_mfma_f32_16x16x32_bf16 v[28:31], v[8:11], v[152:155], v[28:31]
	v_mfma_f32_16x16x32_bf16 v[32:35], v[0:3], v[160:163], v[32:35]
	v_mfma_f32_16x16x32_bf16 v[36:39], v[8:11], v[160:163], v[36:39]
	v_mfma_f32_16x16x32_bf16 v[40:43], v[0:3], v[168:171], v[40:43]
	v_mfma_f32_16x16x32_bf16 v[44:47], v[8:11], v[168:171], v[44:47]
	v_mfma_f32_16x16x32_bf16 v[48:51], v[0:3], v[176:179], v[48:51]
	v_mfma_f32_16x16x32_bf16 v[52:55], v[8:11], v[176:179], v[52:55]
	v_mfma_f32_16x16x32_bf16 v[24:27], v[4:7], v[156:159], v[24:27]
	v_mfma_f32_16x16x32_bf16 v[28:31], v[12:15], v[156:159], v[28:31]
	v_mfma_f32_16x16x32_bf16 v[32:35], v[4:7], v[164:167], v[32:35]
	v_mfma_f32_16x16x32_bf16 v[36:39], v[12:15], v[164:167], v[36:39]
	v_mfma_f32_16x16x32_bf16 v[40:43], v[4:7], v[172:175], v[40:43]
	v_mfma_f32_16x16x32_bf16 v[44:47], v[12:15], v[172:175], v[44:47]
	v_mfma_f32_16x16x32_bf16 v[48:51], v[4:7], v[180:183], v[48:51]
	v_mfma_f32_16x16x32_bf16 v[52:55], v[12:15], v[180:183], v[52:55]
	v_mfma_f32_16x16x32_bf16 v[56:59], v[196:199], v[152:155], v[56:59]
	v_mfma_f32_16x16x32_bf16 v[60:63], v[204:207], v[152:155], v[60:63]
	v_mfma_f32_16x16x32_bf16 v[64:67], v[196:199], v[160:163], v[64:67]
	v_mfma_f32_16x16x32_bf16 v[68:71], v[204:207], v[160:163], v[68:71]
	v_mfma_f32_16x16x32_bf16 v[72:75], v[196:199], v[168:171], v[72:75]
	v_mfma_f32_16x16x32_bf16 v[76:79], v[204:207], v[168:171], v[76:79]
	v_mfma_f32_16x16x32_bf16 v[80:83], v[196:199], v[176:179], v[80:83]
	v_mfma_f32_16x16x32_bf16 v[84:87], v[204:207], v[176:179], v[84:87]
	v_mfma_f32_16x16x32_bf16 v[56:59], v[200:203], v[156:159], v[56:59]
	v_mfma_f32_16x16x32_bf16 v[60:63], v[208:211], v[156:159], v[60:63]
	v_mfma_f32_16x16x32_bf16 v[64:67], v[200:203], v[164:167], v[64:67]
	v_mfma_f32_16x16x32_bf16 v[68:71], v[208:211], v[164:167], v[68:71]
	v_mfma_f32_16x16x32_bf16 v[72:75], v[200:203], v[172:175], v[72:75]
	v_mfma_f32_16x16x32_bf16 v[76:79], v[208:211], v[172:175], v[76:79]
	v_mfma_f32_16x16x32_bf16 v[80:83], v[200:203], v[180:183], v[80:83]
	v_mfma_f32_16x16x32_bf16 v[84:87], v[208:211], v[180:183], v[84:87]
	s_setprio 0
	s_barrier
	ds_read_b128 v[152:155], v186 offset:49168
	ds_read_b128 v[156:159], v187 offset:49168
	ds_read_b128 v[160:163], v186 offset:51216
	ds_read_b128 v[164:167], v187 offset:51216
	ds_read_b128 v[168:171], v186 offset:53264
	ds_read_b128 v[172:175], v187 offset:53264
	ds_read_b128 v[176:179], v186 offset:55312
	ds_read_b128 v[180:183], v187 offset:55312
	s_waitcnt lgkmcnt(0)
	s_barrier
	s_setprio 1
	v_mfma_f32_16x16x32_bf16 v[88:91], v[0:3], v[152:155], v[88:91]
	v_mfma_f32_16x16x32_bf16 v[92:95], v[8:11], v[152:155], v[92:95]
	v_mfma_f32_16x16x32_bf16 v[96:99], v[0:3], v[160:163], v[96:99]
	v_mfma_f32_16x16x32_bf16 v[100:103], v[8:11], v[160:163], v[100:103]
	v_mfma_f32_16x16x32_bf16 v[104:107], v[0:3], v[168:171], v[104:107]
	v_mfma_f32_16x16x32_bf16 v[108:111], v[8:11], v[168:171], v[108:111]
	v_mfma_f32_16x16x32_bf16 v[112:115], v[0:3], v[176:179], v[112:115]
	v_mfma_f32_16x16x32_bf16 v[116:119], v[8:11], v[176:179], v[116:119]
	v_mfma_f32_16x16x32_bf16 v[88:91], v[4:7], v[156:159], v[88:91]
	v_mfma_f32_16x16x32_bf16 v[92:95], v[12:15], v[156:159], v[92:95]
	v_mfma_f32_16x16x32_bf16 v[96:99], v[4:7], v[164:167], v[96:99]
	v_mfma_f32_16x16x32_bf16 v[100:103], v[12:15], v[164:167], v[100:103]
	v_mfma_f32_16x16x32_bf16 v[104:107], v[4:7], v[172:175], v[104:107]
	v_mfma_f32_16x16x32_bf16 v[108:111], v[12:15], v[172:175], v[108:111]
	v_mfma_f32_16x16x32_bf16 v[112:115], v[4:7], v[180:183], v[112:115]
	v_mfma_f32_16x16x32_bf16 v[116:119], v[12:15], v[180:183], v[116:119]
	v_mfma_f32_16x16x32_bf16 v[120:123], v[196:199], v[152:155], v[120:123]
	v_mfma_f32_16x16x32_bf16 v[124:127], v[204:207], v[152:155], v[124:127]
	v_mfma_f32_16x16x32_bf16 v[128:131], v[196:199], v[160:163], v[128:131]
	v_mfma_f32_16x16x32_bf16 v[132:135], v[204:207], v[160:163], v[132:135]
	v_mfma_f32_16x16x32_bf16 v[136:139], v[196:199], v[168:171], v[136:139]
	v_mfma_f32_16x16x32_bf16 v[140:143], v[204:207], v[168:171], v[140:143]
	v_mfma_f32_16x16x32_bf16 v[144:147], v[196:199], v[176:179], v[144:147]
	v_mfma_f32_16x16x32_bf16 v[148:151], v[204:207], v[176:179], v[148:151]
	v_mfma_f32_16x16x32_bf16 v[120:123], v[200:203], v[156:159], v[120:123]
	v_mfma_f32_16x16x32_bf16 v[124:127], v[208:211], v[156:159], v[124:127]
	v_mfma_f32_16x16x32_bf16 v[128:131], v[200:203], v[164:167], v[128:131]
	v_mfma_f32_16x16x32_bf16 v[132:135], v[208:211], v[164:167], v[132:135]
	v_mfma_f32_16x16x32_bf16 v[136:139], v[200:203], v[172:175], v[136:139]
	v_mfma_f32_16x16x32_bf16 v[140:143], v[208:211], v[172:175], v[140:143]
	v_mfma_f32_16x16x32_bf16 v[144:147], v[200:203], v[180:183], v[144:147]
	v_mfma_f32_16x16x32_bf16 v[148:151], v[208:211], v[180:183], v[148:151]
	s_setprio 0
	s_barrier
	s_cmp_lg_u32 s33, 0
	s_cbranch_scc1 .Lgu_epi
	s_barrier
